# FFN_IN tile loop: first k-iteration peeled with srcC=0 (no accumulator clears), last k-iteration peeled with the upper-half SwiGLU epilogue issued inside its last memory/MFMA blocks
# speedup vs baseline: 1.0114x; 1.0028x over previous
.LBB0_683:
	s_ashr_i32 s15, s14, 31
	s_lshl_b64 s[16:17], s[14:15], 19
	v_readlane_b32 s18, v254, 8
	v_readlane_b32 s19, v254, 9
	s_add_u32 s16, s18, s16
	s_addc_u32 s17, s19, s17
	s_and_b64 s[18:19], s[6:7], exec
	s_cselect_b32 s15, s17, s21
	s_cselect_b32 s43, s16, s20
	s_ashr_i32 s13, s12, 31
	s_lshl_b64 s[18:19], s[12:13], 19
	s_add_u32 s18, s0, s18
	s_addc_u32 s19, s28, s19
	s_and_b64 s[24:25], s[6:7], exec
	s_cselect_b32 s13, s19, s23
	s_cselect_b32 s47, s18, s22
	s_add_u32 s20, s20, 0x40080
	s_addc_u32 s21, s21, 0
	s_add_u32 s48, s22, 0x100
	s_addc_u32 s49, s23, 0
	s_mov_b32 s50, -2
	s_add_u32 s22, s20, 0xfffc0080
	s_addc_u32 s23, s21, -1
	s_add_i32 s51, 0, 0x10000
	s_cmp_eq_u32 s50, 12
	s_cselect_b32 s25, s15, s23
	s_cselect_b32 s24, s43, s22
	v_add_u32_e32 v140, s51, v143
	s_cselect_b32 s23, s13, s49
	s_cselect_b32 s22, s47, s48
	s_add_i32 s54, 0, 0x14000
	ds_read_b128 v[146:149], v140
	ds_read_b128 v[150:153], v140 offset:1024
	ds_read_b128 v[154:157], v140 offset:2048
	ds_read_b128 v[158:161], v140 offset:3072
	v_add_u32_e32 v140, s54, v143
	ds_read_b128 v[166:169], v140
	ds_read_b128 v[170:173], v140 offset:1024
	ds_read_b128 v[174:177], v140 offset:2048
	ds_read_b128 v[178:181], v140 offset:3072
	v_lshl_add_u64 v[140:141], s[20:21], 0, v[136:137]
	s_add_i32 m0, s36, 0xc000
	ds_read_b128 v[182:185], v145
	ds_read_b128 v[186:189], v145 offset:1024
	ds_read_b128 v[190:193], v145 offset:2048
	ds_read_b128 v[194:197], v145 offset:3072
	ds_read_b128 v[198:201], v145 offset:4096
	ds_read_b128 v[210:213], v145 offset:5120
	ds_read_b128 v[214:217], v145 offset:6144
	ds_read_b128 v[218:221], v145 offset:7168
	global_load_lds_dwordx4 v[140:141], off
	v_lshl_add_u64 v[140:141], s[20:21], 0, v[138:139]
	s_add_i32 m0, s36, 0xe000
	s_nop 0
	global_load_lds_dwordx4 v[140:141], off
	s_waitcnt vmcnt(8)
	s_waitcnt lgkmcnt(0)
	s_barrier
	s_setprio 1
	s_waitcnt lgkmcnt(0)
	v_mfma_f32_16x16x32_bf16 v[126:129], v[146:149], v[182:185], 0
	v_mfma_f32_16x16x32_bf16 v[118:121], v[154:157], v[182:185], 0
	v_mfma_f32_16x16x32_bf16 v[110:113], v[146:149], v[190:193], 0
	v_mfma_f32_16x16x32_bf16 v[102:105], v[154:157], v[190:193], 0
	v_mfma_f32_16x16x32_bf16 v[94:97], v[146:149], v[198:201], 0
	v_mfma_f32_16x16x32_bf16 v[86:89], v[154:157], v[198:201], 0
	v_mfma_f32_16x16x32_bf16 v[78:81], v[146:149], v[214:217], 0
	v_mfma_f32_16x16x32_bf16 v[70:73], v[154:157], v[214:217], 0
	v_mfma_f32_16x16x32_bf16 v[126:129], v[150:153], v[186:189], v[126:129]
	v_mfma_f32_16x16x32_bf16 v[118:121], v[158:161], v[186:189], v[118:121]
	v_mfma_f32_16x16x32_bf16 v[110:113], v[150:153], v[194:197], v[110:113]
	v_mfma_f32_16x16x32_bf16 v[102:105], v[158:161], v[194:197], v[102:105]
	v_mfma_f32_16x16x32_bf16 v[94:97], v[150:153], v[210:213], v[94:97]
	v_mfma_f32_16x16x32_bf16 v[86:89], v[158:161], v[210:213], v[86:89]
	v_mfma_f32_16x16x32_bf16 v[78:81], v[150:153], v[218:221], v[78:81]
	v_mfma_f32_16x16x32_bf16 v[70:73], v[158:161], v[218:221], v[70:73]
	s_setprio 0
	s_setprio 1
	v_mfma_f32_16x16x32_bf16 v[122:125], v[166:169], v[182:185], 0
	v_mfma_f32_16x16x32_bf16 v[114:117], v[174:177], v[182:185], 0
	v_mfma_f32_16x16x32_bf16 v[106:109], v[166:169], v[190:193], 0
	v_mfma_f32_16x16x32_bf16 v[98:101], v[174:177], v[190:193], 0
	v_mfma_f32_16x16x32_bf16 v[90:93], v[166:169], v[198:201], 0
	v_mfma_f32_16x16x32_bf16 v[82:85], v[174:177], v[198:201], 0
	v_mfma_f32_16x16x32_bf16 v[74:77], v[166:169], v[214:217], 0
	v_mfma_f32_16x16x32_bf16 v[66:69], v[174:177], v[214:217], 0
	v_mfma_f32_16x16x32_bf16 v[122:125], v[170:173], v[186:189], v[122:125]
	v_mfma_f32_16x16x32_bf16 v[114:117], v[178:181], v[186:189], v[114:117]
	v_mfma_f32_16x16x32_bf16 v[106:109], v[170:173], v[194:197], v[106:109]
	v_mfma_f32_16x16x32_bf16 v[98:101], v[178:181], v[194:197], v[98:101]
	v_mfma_f32_16x16x32_bf16 v[90:93], v[170:173], v[210:213], v[90:93]
	v_mfma_f32_16x16x32_bf16 v[82:85], v[178:181], v[210:213], v[82:85]
	v_mfma_f32_16x16x32_bf16 v[74:77], v[170:173], v[218:221], v[74:77]
	v_mfma_f32_16x16x32_bf16 v[66:69], v[178:181], v[218:221], v[66:69]
	s_setprio 0
	s_barrier
	s_add_i32 s51, s51, s29
	v_lshl_add_u64 v[140:141], s[22:23], 0, v[0:1]
	s_mov_b32 m0, s51
	ds_read_b128 v[182:185], v145 offset:16384
	ds_read_b128 v[186:189], v145 offset:17408
	ds_read_b128 v[190:193], v145 offset:18432
	ds_read_b128 v[194:197], v145 offset:19456
	ds_read_b128 v[198:201], v145 offset:20480
	ds_read_b128 v[210:213], v145 offset:21504
	ds_read_b128 v[214:217], v145 offset:22528
	ds_read_b128 v[218:221], v145 offset:23552
	global_load_lds_dwordx4 v[140:141], off
	s_add_i32 m0, s51, 0x2000
	s_add_u32 s52, s22, 0x40000
	v_lshl_add_u64 v[202:203], s[22:23], 0, v[130:131]
	s_addc_u32 s53, s23, 0
	s_add_i32 s51, s54, s29
	global_load_lds_dwordx4 v[202:203], off
	v_lshl_add_u64 v[206:207], s[52:53], 0, v[0:1]
	s_mov_b32 m0, s51
	v_lshl_add_u64 v[222:223], s[24:25], 0, v[132:133]
	global_load_lds_dwordx4 v[206:207], off
	v_lshl_add_u64 v[206:207], s[52:53], 0, v[130:131]
	s_add_i32 m0, s51, 0x2000
	s_nop 0
	global_load_lds_dwordx4 v[206:207], off
	v_lshl_add_u64 v[206:207], s[24:25], 0, v[134:135]
	s_mov_b32 m0, s36
	s_nop 0
	global_load_lds_dwordx4 v[206:207], off
	s_mov_b32 m0, s37
	s_nop 0
	global_load_lds_dwordx4 v[222:223], off
	s_waitcnt vmcnt(8)
	s_waitcnt lgkmcnt(0)
	s_barrier
	s_setprio 1
	s_waitcnt lgkmcnt(0)
	v_mfma_f32_16x16x32_bf16 v[62:65], v[146:149], v[182:185], 0
	v_mfma_f32_16x16x32_bf16 v[54:57], v[154:157], v[182:185], 0
	v_mfma_f32_16x16x32_bf16 v[46:49], v[146:149], v[190:193], 0
	v_mfma_f32_16x16x32_bf16 v[38:41], v[154:157], v[190:193], 0
	v_mfma_f32_16x16x32_bf16 v[30:33], v[146:149], v[198:201], 0
	v_mfma_f32_16x16x32_bf16 v[22:25], v[154:157], v[198:201], 0
	v_mfma_f32_16x16x32_bf16 v[14:17], v[146:149], v[214:217], 0
	v_mfma_f32_16x16x32_bf16 v[6:9], v[154:157], v[214:217], 0
	v_mfma_f32_16x16x32_bf16 v[62:65], v[150:153], v[186:189], v[62:65]
	v_mfma_f32_16x16x32_bf16 v[54:57], v[158:161], v[186:189], v[54:57]
	v_mfma_f32_16x16x32_bf16 v[46:49], v[150:153], v[194:197], v[46:49]
	v_mfma_f32_16x16x32_bf16 v[38:41], v[158:161], v[194:197], v[38:41]
	v_mfma_f32_16x16x32_bf16 v[30:33], v[150:153], v[210:213], v[30:33]
	v_mfma_f32_16x16x32_bf16 v[22:25], v[158:161], v[210:213], v[22:25]
	v_mfma_f32_16x16x32_bf16 v[14:17], v[150:153], v[218:221], v[14:17]
	v_mfma_f32_16x16x32_bf16 v[6:9], v[158:161], v[218:221], v[6:9]
	s_setprio 0
	s_setprio 1
	v_mfma_f32_16x16x32_bf16 v[58:61], v[166:169], v[182:185], 0
	v_mfma_f32_16x16x32_bf16 v[50:53], v[174:177], v[182:185], 0
	v_mfma_f32_16x16x32_bf16 v[42:45], v[166:169], v[190:193], 0
	v_mfma_f32_16x16x32_bf16 v[34:37], v[174:177], v[190:193], 0
	v_mfma_f32_16x16x32_bf16 v[26:29], v[166:169], v[198:201], 0
	v_mfma_f32_16x16x32_bf16 v[18:21], v[174:177], v[198:201], 0
	v_mfma_f32_16x16x32_bf16 v[10:13], v[166:169], v[214:217], 0
	v_mfma_f32_16x16x32_bf16 v[2:5], v[174:177], v[214:217], 0
	v_mfma_f32_16x16x32_bf16 v[58:61], v[170:173], v[186:189], v[58:61]
	v_mfma_f32_16x16x32_bf16 v[50:53], v[178:181], v[186:189], v[50:53]
	v_mfma_f32_16x16x32_bf16 v[42:45], v[170:173], v[194:197], v[42:45]
	v_mfma_f32_16x16x32_bf16 v[34:37], v[178:181], v[194:197], v[34:37]
	v_mfma_f32_16x16x32_bf16 v[26:29], v[170:173], v[210:213], v[26:29]
	v_mfma_f32_16x16x32_bf16 v[18:21], v[178:181], v[210:213], v[18:21]
	v_mfma_f32_16x16x32_bf16 v[10:13], v[170:173], v[218:221], v[10:13]
	v_mfma_f32_16x16x32_bf16 v[2:5], v[178:181], v[218:221], v[2:5]
	s_setprio 0
	s_barrier
	s_add_i32 s51, 0, 0x18000
	s_add_i32 s52, 0, 0x1c000
	v_add_u32_e32 v158, s51, v143
	v_add_u32_e32 v178, s52, v143
	ds_read_b128 v[146:149], v158
	ds_read_b128 v[150:153], v158 offset:1024
	ds_read_b128 v[154:157], v158 offset:2048
	ds_read_b128 v[158:161], v158 offset:3072
	ds_read_b128 v[166:169], v178
	ds_read_b128 v[170:173], v178 offset:1024
	ds_read_b128 v[174:177], v178 offset:2048
	ds_read_b128 v[178:181], v178 offset:3072
	s_add_u32 s24, s24, 0x40000
	s_addc_u32 s25, s25, 0
	s_mov_b32 m0, s38
	v_lshl_add_u64 v[224:225], s[24:25], 0, v[134:135]
	ds_read_b128 v[182:185], v145 offset:32768
	ds_read_b128 v[186:189], v145 offset:33792
	ds_read_b128 v[190:193], v145 offset:34816
	ds_read_b128 v[194:197], v145 offset:35840
	ds_read_b128 v[198:201], v145 offset:36864
	ds_read_b128 v[210:213], v145 offset:37888
	ds_read_b128 v[214:217], v145 offset:38912
	ds_read_b128 v[218:221], v145 offset:39936
	global_load_lds_dwordx4 v[224:225], off
	v_lshl_add_u64 v[224:225], s[24:25], 0, v[132:133]
	s_mov_b32 m0, s39
	s_nop 0
	global_load_lds_dwordx4 v[224:225], off
	s_waitcnt vmcnt(8)
	s_waitcnt lgkmcnt(0)
	s_barrier
	s_setprio 1
	s_waitcnt lgkmcnt(0)
	v_mfma_f32_16x16x32_bf16 v[126:129], v[146:149], v[182:185], v[126:129]
	v_mfma_f32_16x16x32_bf16 v[118:121], v[154:157], v[182:185], v[118:121]
	v_mfma_f32_16x16x32_bf16 v[110:113], v[146:149], v[190:193], v[110:113]
	v_mfma_f32_16x16x32_bf16 v[102:105], v[154:157], v[190:193], v[102:105]
	v_mfma_f32_16x16x32_bf16 v[94:97], v[146:149], v[198:201], v[94:97]
	v_mfma_f32_16x16x32_bf16 v[86:89], v[154:157], v[198:201], v[86:89]
	v_mfma_f32_16x16x32_bf16 v[78:81], v[146:149], v[214:217], v[78:81]
	v_mfma_f32_16x16x32_bf16 v[70:73], v[154:157], v[214:217], v[70:73]
	v_mfma_f32_16x16x32_bf16 v[126:129], v[150:153], v[186:189], v[126:129]
	v_mfma_f32_16x16x32_bf16 v[118:121], v[158:161], v[186:189], v[118:121]
	v_mfma_f32_16x16x32_bf16 v[110:113], v[150:153], v[194:197], v[110:113]
	v_mfma_f32_16x16x32_bf16 v[102:105], v[158:161], v[194:197], v[102:105]
	v_mfma_f32_16x16x32_bf16 v[94:97], v[150:153], v[210:213], v[94:97]
	v_mfma_f32_16x16x32_bf16 v[86:89], v[158:161], v[210:213], v[86:89]
	v_mfma_f32_16x16x32_bf16 v[78:81], v[150:153], v[218:221], v[78:81]
	v_mfma_f32_16x16x32_bf16 v[70:73], v[158:161], v[218:221], v[70:73]
	s_setprio 0
	s_setprio 1
	v_mfma_f32_16x16x32_bf16 v[122:125], v[166:169], v[182:185], v[122:125]
	v_mfma_f32_16x16x32_bf16 v[114:117], v[174:177], v[182:185], v[114:117]
	v_mfma_f32_16x16x32_bf16 v[106:109], v[166:169], v[190:193], v[106:109]
	v_mfma_f32_16x16x32_bf16 v[98:101], v[174:177], v[190:193], v[98:101]
	v_mfma_f32_16x16x32_bf16 v[90:93], v[166:169], v[198:201], v[90:93]
	v_mfma_f32_16x16x32_bf16 v[82:85], v[174:177], v[198:201], v[82:85]
	v_mfma_f32_16x16x32_bf16 v[74:77], v[166:169], v[214:217], v[74:77]
	v_mfma_f32_16x16x32_bf16 v[66:69], v[174:177], v[214:217], v[66:69]
	v_mfma_f32_16x16x32_bf16 v[122:125], v[170:173], v[186:189], v[122:125]
	v_mfma_f32_16x16x32_bf16 v[114:117], v[178:181], v[186:189], v[114:117]
	v_mfma_f32_16x16x32_bf16 v[106:109], v[170:173], v[194:197], v[106:109]
	v_mfma_f32_16x16x32_bf16 v[98:101], v[178:181], v[194:197], v[98:101]
	v_mfma_f32_16x16x32_bf16 v[90:93], v[170:173], v[210:213], v[90:93]
	v_mfma_f32_16x16x32_bf16 v[82:85], v[178:181], v[210:213], v[82:85]
	v_mfma_f32_16x16x32_bf16 v[74:77], v[170:173], v[218:221], v[74:77]
	v_mfma_f32_16x16x32_bf16 v[66:69], v[178:181], v[218:221], v[66:69]
	s_setprio 0
	s_barrier
	s_add_i32 s24, s51, s29
	v_lshl_add_u64 v[140:141], v[140:141], 0, s[4:5]
	s_mov_b32 m0, s24
	ds_read_b128 v[182:185], v145 offset:49152
	ds_read_b128 v[186:189], v145 offset:50176
	ds_read_b128 v[190:193], v145 offset:51200
	ds_read_b128 v[194:197], v145 offset:52224
	ds_read_b128 v[198:201], v145 offset:53248
	ds_read_b128 v[210:213], v145 offset:54272
	ds_read_b128 v[214:217], v145 offset:55296
	ds_read_b128 v[218:221], v145 offset:56320
	global_load_lds_dwordx4 v[140:141], off
	s_add_i32 m0, s24, 0x2000
	s_add_u32 s22, s22, 0x40080
	v_lshl_add_u64 v[140:141], v[202:203], 0, s[4:5]
	s_addc_u32 s23, s23, 0
	s_add_i32 s24, s52, s29
	global_load_lds_dwordx4 v[140:141], off
	v_lshl_add_u64 v[140:141], s[22:23], 0, v[0:1]
	s_mov_b32 m0, s24
	s_nop 0
	global_load_lds_dwordx4 v[140:141], off
	v_lshl_add_u64 v[140:141], s[22:23], 0, v[130:131]
	s_add_i32 m0, s24, 0x2000
	s_nop 0
	global_load_lds_dwordx4 v[140:141], off
	v_lshl_add_u64 v[140:141], v[206:207], 0, s[4:5]
	s_mov_b32 m0, s40
	s_nop 0
	global_load_lds_dwordx4 v[140:141], off
	v_lshl_add_u64 v[140:141], v[222:223], 0, s[4:5]
	s_mov_b32 m0, s41
	s_nop 0
	global_load_lds_dwordx4 v[140:141], off
	s_waitcnt vmcnt(8)
	s_waitcnt lgkmcnt(0)
	s_barrier
	s_setprio 1
	s_waitcnt lgkmcnt(0)
	v_mfma_f32_16x16x32_bf16 v[62:65], v[146:149], v[182:185], v[62:65]
	v_mfma_f32_16x16x32_bf16 v[54:57], v[154:157], v[182:185], v[54:57]
	v_mfma_f32_16x16x32_bf16 v[46:49], v[146:149], v[190:193], v[46:49]
	v_mfma_f32_16x16x32_bf16 v[38:41], v[154:157], v[190:193], v[38:41]
	v_mfma_f32_16x16x32_bf16 v[30:33], v[146:149], v[198:201], v[30:33]
	v_mfma_f32_16x16x32_bf16 v[22:25], v[154:157], v[198:201], v[22:25]
	v_mfma_f32_16x16x32_bf16 v[14:17], v[146:149], v[214:217], v[14:17]
	v_mfma_f32_16x16x32_bf16 v[6:9], v[154:157], v[214:217], v[6:9]
	v_mfma_f32_16x16x32_bf16 v[62:65], v[150:153], v[186:189], v[62:65]
	v_mfma_f32_16x16x32_bf16 v[54:57], v[158:161], v[186:189], v[54:57]
	v_mfma_f32_16x16x32_bf16 v[46:49], v[150:153], v[194:197], v[46:49]
	v_mfma_f32_16x16x32_bf16 v[38:41], v[158:161], v[194:197], v[38:41]
	v_mfma_f32_16x16x32_bf16 v[30:33], v[150:153], v[210:213], v[30:33]
	v_mfma_f32_16x16x32_bf16 v[22:25], v[158:161], v[210:213], v[22:25]
	v_mfma_f32_16x16x32_bf16 v[14:17], v[150:153], v[218:221], v[14:17]
	v_mfma_f32_16x16x32_bf16 v[6:9], v[158:161], v[218:221], v[6:9]
	s_setprio 0
	s_setprio 1
	v_mfma_f32_16x16x32_bf16 v[58:61], v[166:169], v[182:185], v[58:61]
	v_mfma_f32_16x16x32_bf16 v[50:53], v[174:177], v[182:185], v[50:53]
	v_mfma_f32_16x16x32_bf16 v[42:45], v[166:169], v[190:193], v[42:45]
	v_mfma_f32_16x16x32_bf16 v[34:37], v[174:177], v[190:193], v[34:37]
	v_mfma_f32_16x16x32_bf16 v[26:29], v[166:169], v[198:201], v[26:29]
	v_mfma_f32_16x16x32_bf16 v[18:21], v[174:177], v[198:201], v[18:21]
	v_mfma_f32_16x16x32_bf16 v[10:13], v[166:169], v[214:217], v[10:13]
	v_mfma_f32_16x16x32_bf16 v[2:5], v[174:177], v[214:217], v[2:5]
	v_mfma_f32_16x16x32_bf16 v[58:61], v[170:173], v[186:189], v[58:61]
	v_mfma_f32_16x16x32_bf16 v[50:53], v[178:181], v[186:189], v[50:53]
	v_mfma_f32_16x16x32_bf16 v[42:45], v[170:173], v[194:197], v[42:45]
	v_mfma_f32_16x16x32_bf16 v[34:37], v[178:181], v[194:197], v[34:37]
	v_mfma_f32_16x16x32_bf16 v[26:29], v[170:173], v[210:213], v[26:29]
	v_mfma_f32_16x16x32_bf16 v[18:21], v[178:181], v[210:213], v[18:21]
	v_mfma_f32_16x16x32_bf16 v[10:13], v[170:173], v[218:221], v[10:13]
	v_mfma_f32_16x16x32_bf16 v[2:5], v[178:181], v[218:221], v[2:5]
	s_setprio 0
	s_barrier
	s_add_i32 s50, s50, 2
	s_add_u32 s20, s20, 0x100
	s_addc_u32 s21, s21, 0
	s_add_u32 s48, s48, 0x100
	s_addc_u32 s49, s49, 0
.LBB0_684:
	s_add_u32 s22, s20, 0xfffc0080
	s_addc_u32 s23, s21, -1
	s_add_i32 s51, 0, 0x10000
	s_cmp_eq_u32 s50, 12
	s_cselect_b32 s25, s15, s23
	s_cselect_b32 s24, s43, s22
	v_add_u32_e32 v140, s51, v143
	s_cselect_b32 s23, s13, s49
	s_cselect_b32 s22, s47, s48
	s_add_i32 s54, 0, 0x14000
	ds_read_b128 v[146:149], v140
	ds_read_b128 v[150:153], v140 offset:1024
	ds_read_b128 v[154:157], v140 offset:2048
	ds_read_b128 v[158:161], v140 offset:3072
	v_add_u32_e32 v140, s54, v143
	ds_read_b128 v[166:169], v140
	ds_read_b128 v[170:173], v140 offset:1024
	ds_read_b128 v[174:177], v140 offset:2048
	ds_read_b128 v[178:181], v140 offset:3072
	v_lshl_add_u64 v[140:141], s[20:21], 0, v[136:137]
	s_add_i32 m0, s36, 0xc000
	ds_read_b128 v[182:185], v145
	ds_read_b128 v[186:189], v145 offset:1024
	ds_read_b128 v[190:193], v145 offset:2048
	ds_read_b128 v[194:197], v145 offset:3072
	ds_read_b128 v[198:201], v145 offset:4096
	ds_read_b128 v[210:213], v145 offset:5120
	ds_read_b128 v[214:217], v145 offset:6144
	ds_read_b128 v[218:221], v145 offset:7168
	global_load_lds_dwordx4 v[140:141], off
	v_lshl_add_u64 v[140:141], s[20:21], 0, v[138:139]
	s_add_i32 m0, s36, 0xe000
	s_nop 0
	global_load_lds_dwordx4 v[140:141], off
	s_waitcnt vmcnt(8)
	s_waitcnt lgkmcnt(0)
	s_barrier
	s_setprio 1
	s_waitcnt lgkmcnt(0)
	v_mfma_f32_16x16x32_bf16 v[126:129], v[146:149], v[182:185], v[126:129]
	v_mfma_f32_16x16x32_bf16 v[118:121], v[154:157], v[182:185], v[118:121]
	v_mfma_f32_16x16x32_bf16 v[110:113], v[146:149], v[190:193], v[110:113]
	v_mfma_f32_16x16x32_bf16 v[102:105], v[154:157], v[190:193], v[102:105]
	v_mfma_f32_16x16x32_bf16 v[94:97], v[146:149], v[198:201], v[94:97]
	v_mfma_f32_16x16x32_bf16 v[86:89], v[154:157], v[198:201], v[86:89]
	v_mfma_f32_16x16x32_bf16 v[78:81], v[146:149], v[214:217], v[78:81]
	v_mfma_f32_16x16x32_bf16 v[70:73], v[154:157], v[214:217], v[70:73]
	v_mfma_f32_16x16x32_bf16 v[126:129], v[150:153], v[186:189], v[126:129]
	v_mfma_f32_16x16x32_bf16 v[118:121], v[158:161], v[186:189], v[118:121]
	v_mfma_f32_16x16x32_bf16 v[110:113], v[150:153], v[194:197], v[110:113]
	v_mfma_f32_16x16x32_bf16 v[102:105], v[158:161], v[194:197], v[102:105]
	v_mfma_f32_16x16x32_bf16 v[94:97], v[150:153], v[210:213], v[94:97]
	v_mfma_f32_16x16x32_bf16 v[86:89], v[158:161], v[210:213], v[86:89]
	v_mfma_f32_16x16x32_bf16 v[78:81], v[150:153], v[218:221], v[78:81]
	v_mfma_f32_16x16x32_bf16 v[70:73], v[158:161], v[218:221], v[70:73]
	s_setprio 0
	s_setprio 1
	v_mfma_f32_16x16x32_bf16 v[122:125], v[166:169], v[182:185], v[122:125]
	v_mfma_f32_16x16x32_bf16 v[114:117], v[174:177], v[182:185], v[114:117]
	v_mfma_f32_16x16x32_bf16 v[106:109], v[166:169], v[190:193], v[106:109]
	v_mfma_f32_16x16x32_bf16 v[98:101], v[174:177], v[190:193], v[98:101]
	v_mfma_f32_16x16x32_bf16 v[90:93], v[166:169], v[198:201], v[90:93]
	v_mfma_f32_16x16x32_bf16 v[82:85], v[174:177], v[198:201], v[82:85]
	v_mfma_f32_16x16x32_bf16 v[74:77], v[166:169], v[214:217], v[74:77]
	v_mfma_f32_16x16x32_bf16 v[66:69], v[174:177], v[214:217], v[66:69]
	v_mfma_f32_16x16x32_bf16 v[122:125], v[170:173], v[186:189], v[122:125]
	v_mfma_f32_16x16x32_bf16 v[114:117], v[178:181], v[186:189], v[114:117]
	v_mfma_f32_16x16x32_bf16 v[106:109], v[170:173], v[194:197], v[106:109]
	v_mfma_f32_16x16x32_bf16 v[98:101], v[178:181], v[194:197], v[98:101]
	v_mfma_f32_16x16x32_bf16 v[90:93], v[170:173], v[210:213], v[90:93]
	v_mfma_f32_16x16x32_bf16 v[82:85], v[178:181], v[210:213], v[82:85]
	v_mfma_f32_16x16x32_bf16 v[74:77], v[170:173], v[218:221], v[74:77]
	v_mfma_f32_16x16x32_bf16 v[66:69], v[178:181], v[218:221], v[66:69]
	s_setprio 0
	s_barrier
	s_add_i32 s51, s51, s29
	v_lshl_add_u64 v[140:141], s[22:23], 0, v[0:1]
	s_mov_b32 m0, s51
	ds_read_b128 v[182:185], v145 offset:16384
	ds_read_b128 v[186:189], v145 offset:17408
	ds_read_b128 v[190:193], v145 offset:18432
	ds_read_b128 v[194:197], v145 offset:19456
	ds_read_b128 v[198:201], v145 offset:20480
	ds_read_b128 v[210:213], v145 offset:21504
	ds_read_b128 v[214:217], v145 offset:22528
	ds_read_b128 v[218:221], v145 offset:23552
	global_load_lds_dwordx4 v[140:141], off
	s_add_i32 m0, s51, 0x2000
	s_add_u32 s52, s22, 0x40000
	v_lshl_add_u64 v[202:203], s[22:23], 0, v[130:131]
	s_addc_u32 s53, s23, 0
	s_add_i32 s51, s54, s29
	global_load_lds_dwordx4 v[202:203], off
	v_lshl_add_u64 v[206:207], s[52:53], 0, v[0:1]
	s_mov_b32 m0, s51
	v_lshl_add_u64 v[222:223], s[24:25], 0, v[132:133]
	global_load_lds_dwordx4 v[206:207], off
	v_lshl_add_u64 v[206:207], s[52:53], 0, v[130:131]
	s_add_i32 m0, s51, 0x2000
	s_nop 0
	global_load_lds_dwordx4 v[206:207], off
	v_lshl_add_u64 v[206:207], s[24:25], 0, v[134:135]
	s_mov_b32 m0, s36
	s_nop 0
	global_load_lds_dwordx4 v[206:207], off
	s_mov_b32 m0, s37
	s_nop 0
	global_load_lds_dwordx4 v[222:223], off
	s_waitcnt vmcnt(8)
	s_waitcnt lgkmcnt(0)
	s_barrier
	s_setprio 1
	s_waitcnt lgkmcnt(0)
	v_mfma_f32_16x16x32_bf16 v[62:65], v[146:149], v[182:185], v[62:65]
	v_mfma_f32_16x16x32_bf16 v[54:57], v[154:157], v[182:185], v[54:57]
	v_mfma_f32_16x16x32_bf16 v[46:49], v[146:149], v[190:193], v[46:49]
	v_mfma_f32_16x16x32_bf16 v[38:41], v[154:157], v[190:193], v[38:41]
	v_mfma_f32_16x16x32_bf16 v[30:33], v[146:149], v[198:201], v[30:33]
	v_mfma_f32_16x16x32_bf16 v[22:25], v[154:157], v[198:201], v[22:25]
	v_mfma_f32_16x16x32_bf16 v[14:17], v[146:149], v[214:217], v[14:17]
	v_mfma_f32_16x16x32_bf16 v[6:9], v[154:157], v[214:217], v[6:9]
	v_mfma_f32_16x16x32_bf16 v[62:65], v[150:153], v[186:189], v[62:65]
	v_mfma_f32_16x16x32_bf16 v[54:57], v[158:161], v[186:189], v[54:57]
	v_mfma_f32_16x16x32_bf16 v[46:49], v[150:153], v[194:197], v[46:49]
	v_mfma_f32_16x16x32_bf16 v[38:41], v[158:161], v[194:197], v[38:41]
	v_mfma_f32_16x16x32_bf16 v[30:33], v[150:153], v[210:213], v[30:33]
	v_mfma_f32_16x16x32_bf16 v[22:25], v[158:161], v[210:213], v[22:25]
	v_mfma_f32_16x16x32_bf16 v[14:17], v[150:153], v[218:221], v[14:17]
	v_mfma_f32_16x16x32_bf16 v[6:9], v[158:161], v[218:221], v[6:9]
	s_setprio 0
	s_setprio 1
	v_mfma_f32_16x16x32_bf16 v[58:61], v[166:169], v[182:185], v[58:61]
	v_mfma_f32_16x16x32_bf16 v[50:53], v[174:177], v[182:185], v[50:53]
	v_mfma_f32_16x16x32_bf16 v[42:45], v[166:169], v[190:193], v[42:45]
	v_mfma_f32_16x16x32_bf16 v[34:37], v[174:177], v[190:193], v[34:37]
	v_mfma_f32_16x16x32_bf16 v[26:29], v[166:169], v[198:201], v[26:29]
	v_mfma_f32_16x16x32_bf16 v[18:21], v[174:177], v[198:201], v[18:21]
	v_mfma_f32_16x16x32_bf16 v[10:13], v[166:169], v[214:217], v[10:13]
	v_mfma_f32_16x16x32_bf16 v[2:5], v[174:177], v[214:217], v[2:5]
	v_mfma_f32_16x16x32_bf16 v[58:61], v[170:173], v[186:189], v[58:61]
	v_mfma_f32_16x16x32_bf16 v[50:53], v[178:181], v[186:189], v[50:53]
	v_mfma_f32_16x16x32_bf16 v[42:45], v[170:173], v[194:197], v[42:45]
	v_mfma_f32_16x16x32_bf16 v[34:37], v[178:181], v[194:197], v[34:37]
	v_mfma_f32_16x16x32_bf16 v[26:29], v[170:173], v[210:213], v[26:29]
	v_mfma_f32_16x16x32_bf16 v[18:21], v[178:181], v[210:213], v[18:21]
	v_mfma_f32_16x16x32_bf16 v[10:13], v[170:173], v[218:221], v[10:13]
	v_mfma_f32_16x16x32_bf16 v[2:5], v[178:181], v[218:221], v[2:5]
	s_setprio 0
	s_barrier
	s_add_i32 s51, 0, 0x18000
	s_add_i32 s52, 0, 0x1c000
	v_add_u32_e32 v158, s51, v143
	v_add_u32_e32 v178, s52, v143
	ds_read_b128 v[146:149], v158
	ds_read_b128 v[150:153], v158 offset:1024
	ds_read_b128 v[154:157], v158 offset:2048
	ds_read_b128 v[158:161], v158 offset:3072
	ds_read_b128 v[166:169], v178
	ds_read_b128 v[170:173], v178 offset:1024
	ds_read_b128 v[174:177], v178 offset:2048
	ds_read_b128 v[178:181], v178 offset:3072
	s_add_u32 s24, s24, 0x40000
	s_addc_u32 s25, s25, 0
	s_mov_b32 m0, s38
	v_lshl_add_u64 v[224:225], s[24:25], 0, v[134:135]
	ds_read_b128 v[182:185], v145 offset:32768
	ds_read_b128 v[186:189], v145 offset:33792
	ds_read_b128 v[190:193], v145 offset:34816
	ds_read_b128 v[194:197], v145 offset:35840
	ds_read_b128 v[198:201], v145 offset:36864
	ds_read_b128 v[210:213], v145 offset:37888
	ds_read_b128 v[214:217], v145 offset:38912
	ds_read_b128 v[218:221], v145 offset:39936
	global_load_lds_dwordx4 v[224:225], off
	v_lshl_add_u64 v[224:225], s[24:25], 0, v[132:133]
	s_mov_b32 m0, s39
	s_nop 0
	global_load_lds_dwordx4 v[224:225], off
	s_waitcnt vmcnt(8)
	s_waitcnt lgkmcnt(0)
	s_barrier
	s_setprio 1
	s_waitcnt lgkmcnt(0)
	v_mfma_f32_16x16x32_bf16 v[126:129], v[146:149], v[182:185], v[126:129]
	v_mfma_f32_16x16x32_bf16 v[118:121], v[154:157], v[182:185], v[118:121]
	v_mfma_f32_16x16x32_bf16 v[110:113], v[146:149], v[190:193], v[110:113]
	v_mfma_f32_16x16x32_bf16 v[102:105], v[154:157], v[190:193], v[102:105]
	v_mfma_f32_16x16x32_bf16 v[94:97], v[146:149], v[198:201], v[94:97]
	v_mfma_f32_16x16x32_bf16 v[86:89], v[154:157], v[198:201], v[86:89]
	v_mfma_f32_16x16x32_bf16 v[78:81], v[146:149], v[214:217], v[78:81]
	v_mfma_f32_16x16x32_bf16 v[70:73], v[154:157], v[214:217], v[70:73]
	v_mfma_f32_16x16x32_bf16 v[126:129], v[150:153], v[186:189], v[126:129]
	v_mfma_f32_16x16x32_bf16 v[118:121], v[158:161], v[186:189], v[118:121]
	v_mfma_f32_16x16x32_bf16 v[110:113], v[150:153], v[194:197], v[110:113]
	v_mfma_f32_16x16x32_bf16 v[102:105], v[158:161], v[194:197], v[102:105]
	v_mfma_f32_16x16x32_bf16 v[94:97], v[150:153], v[210:213], v[94:97]
	v_mfma_f32_16x16x32_bf16 v[86:89], v[158:161], v[210:213], v[86:89]
	v_mfma_f32_16x16x32_bf16 v[78:81], v[150:153], v[218:221], v[78:81]
	v_mfma_f32_16x16x32_bf16 v[70:73], v[158:161], v[218:221], v[70:73]
	s_setprio 0
	s_setprio 1
	v_mfma_f32_16x16x32_bf16 v[122:125], v[166:169], v[182:185], v[122:125]
	v_mfma_f32_16x16x32_bf16 v[114:117], v[174:177], v[182:185], v[114:117]
	v_mfma_f32_16x16x32_bf16 v[106:109], v[166:169], v[190:193], v[106:109]
	v_mfma_f32_16x16x32_bf16 v[98:101], v[174:177], v[190:193], v[98:101]
	v_mfma_f32_16x16x32_bf16 v[90:93], v[166:169], v[198:201], v[90:93]
	v_mfma_f32_16x16x32_bf16 v[82:85], v[174:177], v[198:201], v[82:85]
	v_mfma_f32_16x16x32_bf16 v[74:77], v[166:169], v[214:217], v[74:77]
	v_mfma_f32_16x16x32_bf16 v[66:69], v[174:177], v[214:217], v[66:69]
	v_mfma_f32_16x16x32_bf16 v[122:125], v[170:173], v[186:189], v[122:125]
	v_mfma_f32_16x16x32_bf16 v[114:117], v[178:181], v[186:189], v[114:117]
	v_mfma_f32_16x16x32_bf16 v[106:109], v[170:173], v[194:197], v[106:109]
	v_mfma_f32_16x16x32_bf16 v[98:101], v[178:181], v[194:197], v[98:101]
	v_mfma_f32_16x16x32_bf16 v[90:93], v[170:173], v[210:213], v[90:93]
	v_mfma_f32_16x16x32_bf16 v[82:85], v[178:181], v[210:213], v[82:85]
	v_mfma_f32_16x16x32_bf16 v[74:77], v[170:173], v[218:221], v[74:77]
	v_mfma_f32_16x16x32_bf16 v[66:69], v[178:181], v[218:221], v[66:69]
	s_setprio 0
	s_barrier
	s_add_i32 s24, s51, s29
	v_lshl_add_u64 v[140:141], v[140:141], 0, s[4:5]
	s_mov_b32 m0, s24
	ds_read_b128 v[182:185], v145 offset:49152
	ds_read_b128 v[186:189], v145 offset:50176
	ds_read_b128 v[190:193], v145 offset:51200
	ds_read_b128 v[194:197], v145 offset:52224
	ds_read_b128 v[198:201], v145 offset:53248
	ds_read_b128 v[210:213], v145 offset:54272
	ds_read_b128 v[214:217], v145 offset:55296
	ds_read_b128 v[218:221], v145 offset:56320
	global_load_lds_dwordx4 v[140:141], off
	s_add_i32 m0, s24, 0x2000
	s_add_u32 s22, s22, 0x40080
	v_lshl_add_u64 v[140:141], v[202:203], 0, s[4:5]
	s_addc_u32 s23, s23, 0
	s_add_i32 s24, s52, s29
	global_load_lds_dwordx4 v[140:141], off
	v_lshl_add_u64 v[140:141], s[22:23], 0, v[0:1]
	s_mov_b32 m0, s24
	s_nop 0
	global_load_lds_dwordx4 v[140:141], off
	v_lshl_add_u64 v[140:141], s[22:23], 0, v[130:131]
	s_add_i32 m0, s24, 0x2000
	s_nop 0
	global_load_lds_dwordx4 v[140:141], off
	v_lshl_add_u64 v[140:141], v[206:207], 0, s[4:5]
	s_mov_b32 m0, s40
	s_nop 0
	global_load_lds_dwordx4 v[140:141], off
	v_lshl_add_u64 v[140:141], v[222:223], 0, s[4:5]
	s_mov_b32 m0, s41
	s_nop 0
	global_load_lds_dwordx4 v[140:141], off
	s_waitcnt vmcnt(8)
	s_waitcnt lgkmcnt(0)
	s_barrier
	s_setprio 1
	s_waitcnt lgkmcnt(0)
	v_mfma_f32_16x16x32_bf16 v[62:65], v[146:149], v[182:185], v[62:65]
	v_mfma_f32_16x16x32_bf16 v[54:57], v[154:157], v[182:185], v[54:57]
	v_mfma_f32_16x16x32_bf16 v[46:49], v[146:149], v[190:193], v[46:49]
	v_mfma_f32_16x16x32_bf16 v[38:41], v[154:157], v[190:193], v[38:41]
	v_mfma_f32_16x16x32_bf16 v[30:33], v[146:149], v[198:201], v[30:33]
	v_mfma_f32_16x16x32_bf16 v[22:25], v[154:157], v[198:201], v[22:25]
	v_mfma_f32_16x16x32_bf16 v[14:17], v[146:149], v[214:217], v[14:17]
	v_mfma_f32_16x16x32_bf16 v[6:9], v[154:157], v[214:217], v[6:9]
	v_mfma_f32_16x16x32_bf16 v[62:65], v[150:153], v[186:189], v[62:65]
	v_mfma_f32_16x16x32_bf16 v[54:57], v[158:161], v[186:189], v[54:57]
	v_mfma_f32_16x16x32_bf16 v[46:49], v[150:153], v[194:197], v[46:49]
	v_mfma_f32_16x16x32_bf16 v[38:41], v[158:161], v[194:197], v[38:41]
	v_mfma_f32_16x16x32_bf16 v[30:33], v[150:153], v[210:213], v[30:33]
	v_mfma_f32_16x16x32_bf16 v[22:25], v[158:161], v[210:213], v[22:25]
	v_mfma_f32_16x16x32_bf16 v[14:17], v[150:153], v[218:221], v[14:17]
	v_mfma_f32_16x16x32_bf16 v[6:9], v[158:161], v[218:221], v[6:9]
	s_setprio 0
	s_setprio 1
	v_mfma_f32_16x16x32_bf16 v[58:61], v[166:169], v[182:185], v[58:61]
	v_mfma_f32_16x16x32_bf16 v[50:53], v[174:177], v[182:185], v[50:53]
	v_mfma_f32_16x16x32_bf16 v[42:45], v[166:169], v[190:193], v[42:45]
	v_mfma_f32_16x16x32_bf16 v[34:37], v[174:177], v[190:193], v[34:37]
	v_mfma_f32_16x16x32_bf16 v[26:29], v[166:169], v[198:201], v[26:29]
	v_mfma_f32_16x16x32_bf16 v[18:21], v[174:177], v[198:201], v[18:21]
	v_mfma_f32_16x16x32_bf16 v[10:13], v[166:169], v[214:217], v[10:13]
	v_mfma_f32_16x16x32_bf16 v[2:5], v[174:177], v[214:217], v[2:5]
	v_mfma_f32_16x16x32_bf16 v[58:61], v[170:173], v[186:189], v[58:61]
	v_mfma_f32_16x16x32_bf16 v[50:53], v[178:181], v[186:189], v[50:53]
	v_mfma_f32_16x16x32_bf16 v[42:45], v[170:173], v[194:197], v[42:45]
	v_mfma_f32_16x16x32_bf16 v[34:37], v[178:181], v[194:197], v[34:37]
	v_mfma_f32_16x16x32_bf16 v[26:29], v[170:173], v[210:213], v[26:29]
	v_mfma_f32_16x16x32_bf16 v[18:21], v[178:181], v[210:213], v[18:21]
	v_mfma_f32_16x16x32_bf16 v[10:13], v[170:173], v[218:221], v[10:13]
	v_mfma_f32_16x16x32_bf16 v[2:5], v[178:181], v[218:221], v[2:5]
	s_setprio 0
	s_barrier
	s_add_i32 s50, s50, 2
	s_add_u32 s20, s20, 0x100
	s_addc_u32 s21, s21, 0
	s_add_u32 s48, s48, 0x100
	s_addc_u32 s49, s49, 0
	s_cmp_gt_u32 s50, 11
	s_cbranch_scc0 .LBB0_684
	v_readlane_b32 s100, v254, 12
	v_readlane_b32 s101, v254, 13
	v_lshl_add_u32 v246, s35, 8, v142
	v_lshl_or_b32 v247, s34, 7, v144
	v_mov_b32_e32 v244, 0xbfb8aa3b
	v_mov_b32_e32 v245, 0xbfb8aa3b
	v_mul_u32_u24_e32 v246, 0x1600, v246
	v_lshl_add_u32 v246, v247, 1, v246
	s_add_u32 s22, s20, 0xfffc0080
	s_addc_u32 s23, s21, -1
	s_add_i32 s51, 0, 0x10000
	s_cmp_eq_u32 s50, 12
	s_cselect_b32 s25, s15, s23
	s_cselect_b32 s24, s43, s22
	v_add_u32_e32 v140, s51, v143
	s_cselect_b32 s23, s13, s49
	s_cselect_b32 s22, s47, s48
	s_add_i32 s54, 0, 0x14000
	ds_read_b128 v[146:149], v140
	ds_read_b128 v[150:153], v140 offset:1024
	ds_read_b128 v[154:157], v140 offset:2048
	ds_read_b128 v[158:161], v140 offset:3072
	v_add_u32_e32 v140, s54, v143
	ds_read_b128 v[166:169], v140
	ds_read_b128 v[170:173], v140 offset:1024
	ds_read_b128 v[174:177], v140 offset:2048
	ds_read_b128 v[178:181], v140 offset:3072
	v_lshl_add_u64 v[140:141], s[20:21], 0, v[136:137]
	s_add_i32 m0, s36, 0xc000
	ds_read_b128 v[182:185], v145
	ds_read_b128 v[186:189], v145 offset:1024
	ds_read_b128 v[190:193], v145 offset:2048
	ds_read_b128 v[194:197], v145 offset:3072
	ds_read_b128 v[198:201], v145 offset:4096
	ds_read_b128 v[210:213], v145 offset:5120
	ds_read_b128 v[214:217], v145 offset:6144
	ds_read_b128 v[218:221], v145 offset:7168
	global_load_lds_dwordx4 v[140:141], off
	v_lshl_add_u64 v[140:141], s[20:21], 0, v[138:139]
	s_add_i32 m0, s36, 0xe000
	s_nop 0
	global_load_lds_dwordx4 v[140:141], off
	s_waitcnt vmcnt(8)
	s_waitcnt lgkmcnt(0)
	s_barrier
	s_setprio 1
	s_waitcnt lgkmcnt(0)
	v_mfma_f32_16x16x32_bf16 v[126:129], v[146:149], v[182:185], v[126:129]
	v_mfma_f32_16x16x32_bf16 v[118:121], v[154:157], v[182:185], v[118:121]
	v_mfma_f32_16x16x32_bf16 v[110:113], v[146:149], v[190:193], v[110:113]
	v_mfma_f32_16x16x32_bf16 v[102:105], v[154:157], v[190:193], v[102:105]
	v_mfma_f32_16x16x32_bf16 v[94:97], v[146:149], v[198:201], v[94:97]
	v_mfma_f32_16x16x32_bf16 v[86:89], v[154:157], v[198:201], v[86:89]
	v_mfma_f32_16x16x32_bf16 v[78:81], v[146:149], v[214:217], v[78:81]
	v_mfma_f32_16x16x32_bf16 v[70:73], v[154:157], v[214:217], v[70:73]
	v_mfma_f32_16x16x32_bf16 v[126:129], v[150:153], v[186:189], v[126:129]
	v_mfma_f32_16x16x32_bf16 v[118:121], v[158:161], v[186:189], v[118:121]
	v_mfma_f32_16x16x32_bf16 v[110:113], v[150:153], v[194:197], v[110:113]
	v_mfma_f32_16x16x32_bf16 v[102:105], v[158:161], v[194:197], v[102:105]
	v_mfma_f32_16x16x32_bf16 v[94:97], v[150:153], v[210:213], v[94:97]
	v_mfma_f32_16x16x32_bf16 v[86:89], v[158:161], v[210:213], v[86:89]
	v_mfma_f32_16x16x32_bf16 v[78:81], v[150:153], v[218:221], v[78:81]
	v_mfma_f32_16x16x32_bf16 v[70:73], v[158:161], v[218:221], v[70:73]
	s_setprio 0
	s_setprio 1
	v_mfma_f32_16x16x32_bf16 v[122:125], v[166:169], v[182:185], v[122:125]
	v_mfma_f32_16x16x32_bf16 v[114:117], v[174:177], v[182:185], v[114:117]
	v_mfma_f32_16x16x32_bf16 v[106:109], v[166:169], v[190:193], v[106:109]
	v_mfma_f32_16x16x32_bf16 v[98:101], v[174:177], v[190:193], v[98:101]
	v_mfma_f32_16x16x32_bf16 v[90:93], v[166:169], v[198:201], v[90:93]
	v_mfma_f32_16x16x32_bf16 v[82:85], v[174:177], v[198:201], v[82:85]
	v_mfma_f32_16x16x32_bf16 v[74:77], v[166:169], v[214:217], v[74:77]
	v_mfma_f32_16x16x32_bf16 v[66:69], v[174:177], v[214:217], v[66:69]
	v_mfma_f32_16x16x32_bf16 v[122:125], v[170:173], v[186:189], v[122:125]
	v_mfma_f32_16x16x32_bf16 v[114:117], v[178:181], v[186:189], v[114:117]
	v_mfma_f32_16x16x32_bf16 v[106:109], v[170:173], v[194:197], v[106:109]
	v_mfma_f32_16x16x32_bf16 v[98:101], v[178:181], v[194:197], v[98:101]
	v_mfma_f32_16x16x32_bf16 v[90:93], v[170:173], v[210:213], v[90:93]
	v_mfma_f32_16x16x32_bf16 v[82:85], v[178:181], v[210:213], v[82:85]
	v_mfma_f32_16x16x32_bf16 v[74:77], v[170:173], v[218:221], v[74:77]
	v_mfma_f32_16x16x32_bf16 v[66:69], v[178:181], v[218:221], v[66:69]
	s_setprio 0
	s_barrier
	s_add_i32 s51, s51, s29
	v_lshl_add_u64 v[140:141], s[22:23], 0, v[0:1]
	s_mov_b32 m0, s51
	ds_read_b128 v[182:185], v145 offset:16384
	ds_read_b128 v[186:189], v145 offset:17408
	ds_read_b128 v[190:193], v145 offset:18432
	ds_read_b128 v[194:197], v145 offset:19456
	ds_read_b128 v[198:201], v145 offset:20480
	ds_read_b128 v[210:213], v145 offset:21504
	ds_read_b128 v[214:217], v145 offset:22528
	ds_read_b128 v[218:221], v145 offset:23552
	global_load_lds_dwordx4 v[140:141], off
	s_add_i32 m0, s51, 0x2000
	s_add_u32 s52, s22, 0x40000
	v_lshl_add_u64 v[202:203], s[22:23], 0, v[130:131]
	s_addc_u32 s53, s23, 0
	s_add_i32 s51, s54, s29
	global_load_lds_dwordx4 v[202:203], off
	v_lshl_add_u64 v[206:207], s[52:53], 0, v[0:1]
	s_mov_b32 m0, s51
	v_lshl_add_u64 v[222:223], s[24:25], 0, v[132:133]
	global_load_lds_dwordx4 v[206:207], off
	v_lshl_add_u64 v[206:207], s[52:53], 0, v[130:131]
	s_add_i32 m0, s51, 0x2000
	s_nop 0
	global_load_lds_dwordx4 v[206:207], off
	v_lshl_add_u64 v[206:207], s[24:25], 0, v[134:135]
	s_mov_b32 m0, s36
	s_nop 0
	global_load_lds_dwordx4 v[206:207], off
	s_mov_b32 m0, s37
	s_nop 0
	global_load_lds_dwordx4 v[222:223], off
	s_waitcnt vmcnt(8)
	s_waitcnt lgkmcnt(0)
	s_barrier
	s_setprio 1
	s_waitcnt lgkmcnt(0)
	v_mfma_f32_16x16x32_bf16 v[62:65], v[146:149], v[182:185], v[62:65]
	v_mfma_f32_16x16x32_bf16 v[54:57], v[154:157], v[182:185], v[54:57]
	v_mfma_f32_16x16x32_bf16 v[46:49], v[146:149], v[190:193], v[46:49]
	v_mfma_f32_16x16x32_bf16 v[38:41], v[154:157], v[190:193], v[38:41]
	v_mfma_f32_16x16x32_bf16 v[30:33], v[146:149], v[198:201], v[30:33]
	v_mfma_f32_16x16x32_bf16 v[22:25], v[154:157], v[198:201], v[22:25]
	v_mfma_f32_16x16x32_bf16 v[14:17], v[146:149], v[214:217], v[14:17]
	v_mfma_f32_16x16x32_bf16 v[6:9], v[154:157], v[214:217], v[6:9]
	v_mfma_f32_16x16x32_bf16 v[62:65], v[150:153], v[186:189], v[62:65]
	v_mfma_f32_16x16x32_bf16 v[54:57], v[158:161], v[186:189], v[54:57]
	v_mfma_f32_16x16x32_bf16 v[46:49], v[150:153], v[194:197], v[46:49]
	v_mfma_f32_16x16x32_bf16 v[38:41], v[158:161], v[194:197], v[38:41]
	v_mfma_f32_16x16x32_bf16 v[30:33], v[150:153], v[210:213], v[30:33]
	v_mfma_f32_16x16x32_bf16 v[22:25], v[158:161], v[210:213], v[22:25]
	v_mfma_f32_16x16x32_bf16 v[14:17], v[150:153], v[218:221], v[14:17]
	v_mfma_f32_16x16x32_bf16 v[6:9], v[158:161], v[218:221], v[6:9]
	s_setprio 0
	s_setprio 1
	v_mfma_f32_16x16x32_bf16 v[58:61], v[166:169], v[182:185], v[58:61]
	v_mfma_f32_16x16x32_bf16 v[50:53], v[174:177], v[182:185], v[50:53]
	v_mfma_f32_16x16x32_bf16 v[42:45], v[166:169], v[190:193], v[42:45]
	v_mfma_f32_16x16x32_bf16 v[34:37], v[174:177], v[190:193], v[34:37]
	v_mfma_f32_16x16x32_bf16 v[26:29], v[166:169], v[198:201], v[26:29]
	v_mfma_f32_16x16x32_bf16 v[18:21], v[174:177], v[198:201], v[18:21]
	v_mfma_f32_16x16x32_bf16 v[10:13], v[166:169], v[214:217], v[10:13]
	v_mfma_f32_16x16x32_bf16 v[2:5], v[174:177], v[214:217], v[2:5]
	v_mfma_f32_16x16x32_bf16 v[58:61], v[170:173], v[186:189], v[58:61]
	v_mfma_f32_16x16x32_bf16 v[50:53], v[178:181], v[186:189], v[50:53]
	v_mfma_f32_16x16x32_bf16 v[42:45], v[170:173], v[194:197], v[42:45]
	v_mfma_f32_16x16x32_bf16 v[34:37], v[178:181], v[194:197], v[34:37]
	v_mfma_f32_16x16x32_bf16 v[26:29], v[170:173], v[210:213], v[26:29]
	v_mfma_f32_16x16x32_bf16 v[18:21], v[178:181], v[210:213], v[18:21]
	v_mfma_f32_16x16x32_bf16 v[10:13], v[170:173], v[218:221], v[10:13]
	v_mfma_f32_16x16x32_bf16 v[2:5], v[178:181], v[218:221], v[2:5]
	s_setprio 0
	s_barrier
	s_add_i32 s51, 0, 0x18000
	s_add_i32 s52, 0, 0x1c000
	v_add_u32_e32 v158, s51, v143
	v_add_u32_e32 v178, s52, v143
	ds_read_b128 v[146:149], v158
	ds_read_b128 v[150:153], v158 offset:1024
	ds_read_b128 v[154:157], v158 offset:2048
	ds_read_b128 v[158:161], v158 offset:3072
	ds_read_b128 v[166:169], v178
	ds_read_b128 v[170:173], v178 offset:1024
	ds_read_b128 v[174:177], v178 offset:2048
	ds_read_b128 v[178:181], v178 offset:3072
	s_add_u32 s24, s24, 0x40000
	s_addc_u32 s25, s25, 0
	s_mov_b32 m0, s38
	v_lshl_add_u64 v[224:225], s[24:25], 0, v[134:135]
	ds_read_b128 v[182:185], v145 offset:32768
	ds_read_b128 v[186:189], v145 offset:33792
	ds_read_b128 v[190:193], v145 offset:34816
	ds_read_b128 v[194:197], v145 offset:35840
	ds_read_b128 v[198:201], v145 offset:36864
	ds_read_b128 v[210:213], v145 offset:37888
	ds_read_b128 v[214:217], v145 offset:38912
	ds_read_b128 v[218:221], v145 offset:39936
	global_load_lds_dwordx4 v[224:225], off
	v_lshl_add_u64 v[224:225], s[24:25], 0, v[132:133]
	s_mov_b32 m0, s39
	s_nop 0
	global_load_lds_dwordx4 v[224:225], off
	s_waitcnt vmcnt(8)
	s_waitcnt lgkmcnt(0)
	s_barrier
	s_setprio 1
	s_waitcnt lgkmcnt(0)
	v_mfma_f32_16x16x32_bf16 v[126:129], v[146:149], v[182:185], v[126:129]
	v_mfma_f32_16x16x32_bf16 v[118:121], v[154:157], v[182:185], v[118:121]
	v_mfma_f32_16x16x32_bf16 v[110:113], v[146:149], v[190:193], v[110:113]
	v_mfma_f32_16x16x32_bf16 v[102:105], v[154:157], v[190:193], v[102:105]
	v_mfma_f32_16x16x32_bf16 v[94:97], v[146:149], v[198:201], v[94:97]
	v_mfma_f32_16x16x32_bf16 v[86:89], v[154:157], v[198:201], v[86:89]
	v_mfma_f32_16x16x32_bf16 v[78:81], v[146:149], v[214:217], v[78:81]
	v_mfma_f32_16x16x32_bf16 v[70:73], v[154:157], v[214:217], v[70:73]
	v_mfma_f32_16x16x32_bf16 v[126:129], v[150:153], v[186:189], v[126:129]
	v_mfma_f32_16x16x32_bf16 v[118:121], v[158:161], v[186:189], v[118:121]
	v_mfma_f32_16x16x32_bf16 v[110:113], v[150:153], v[194:197], v[110:113]
	v_mfma_f32_16x16x32_bf16 v[102:105], v[158:161], v[194:197], v[102:105]
	v_mfma_f32_16x16x32_bf16 v[94:97], v[150:153], v[210:213], v[94:97]
	v_mfma_f32_16x16x32_bf16 v[86:89], v[158:161], v[210:213], v[86:89]
	v_mfma_f32_16x16x32_bf16 v[78:81], v[150:153], v[218:221], v[78:81]
	v_mfma_f32_16x16x32_bf16 v[70:73], v[158:161], v[218:221], v[70:73]
	s_setprio 0
	s_setprio 1
	v_mfma_f32_16x16x32_bf16 v[122:125], v[166:169], v[182:185], v[122:125]
	v_mfma_f32_16x16x32_bf16 v[114:117], v[174:177], v[182:185], v[114:117]
	v_mfma_f32_16x16x32_bf16 v[106:109], v[166:169], v[190:193], v[106:109]
	v_mfma_f32_16x16x32_bf16 v[98:101], v[174:177], v[190:193], v[98:101]
	v_mfma_f32_16x16x32_bf16 v[90:93], v[166:169], v[198:201], v[90:93]
	v_mfma_f32_16x16x32_bf16 v[82:85], v[174:177], v[198:201], v[82:85]
	v_mfma_f32_16x16x32_bf16 v[74:77], v[166:169], v[214:217], v[74:77]
	v_mfma_f32_16x16x32_bf16 v[66:69], v[174:177], v[214:217], v[66:69]
	v_mfma_f32_16x16x32_bf16 v[122:125], v[170:173], v[186:189], v[122:125]
	v_mfma_f32_16x16x32_bf16 v[114:117], v[178:181], v[186:189], v[114:117]
	v_mfma_f32_16x16x32_bf16 v[106:109], v[170:173], v[194:197], v[106:109]
	v_mfma_f32_16x16x32_bf16 v[98:101], v[178:181], v[194:197], v[98:101]
	v_mfma_f32_16x16x32_bf16 v[90:93], v[170:173], v[210:213], v[90:93]
	v_mfma_f32_16x16x32_bf16 v[82:85], v[178:181], v[210:213], v[82:85]
	v_mfma_f32_16x16x32_bf16 v[74:77], v[170:173], v[218:221], v[74:77]
	v_mfma_f32_16x16x32_bf16 v[66:69], v[178:181], v[218:221], v[66:69]
	s_setprio 0
	s_barrier
	s_add_i32 s24, s51, s29
	v_lshl_add_u64 v[140:141], v[140:141], 0, s[4:5]
	s_mov_b32 m0, s24
	ds_read_b128 v[182:185], v145 offset:49152
	ds_read_b128 v[186:189], v145 offset:50176
	ds_read_b128 v[190:193], v145 offset:51200
	ds_read_b128 v[194:197], v145 offset:52224
	ds_read_b128 v[198:201], v145 offset:53248
	ds_read_b128 v[210:213], v145 offset:54272
	ds_read_b128 v[214:217], v145 offset:55296
	ds_read_b128 v[218:221], v145 offset:56320
	global_load_lds_dwordx4 v[140:141], off
	s_add_i32 m0, s24, 0x2000
	s_add_u32 s22, s22, 0x40080
	v_lshl_add_u64 v[140:141], v[202:203], 0, s[4:5]
	s_addc_u32 s23, s23, 0
	s_add_i32 s24, s52, s29
	global_load_lds_dwordx4 v[140:141], off
	v_lshl_add_u64 v[140:141], s[22:23], 0, v[0:1]
	s_mov_b32 m0, s24
	s_nop 0
	global_load_lds_dwordx4 v[140:141], off
	v_lshl_add_u64 v[140:141], s[22:23], 0, v[130:131]
	s_add_i32 m0, s24, 0x2000
	s_nop 0
	global_load_lds_dwordx4 v[140:141], off
	v_lshl_add_u64 v[140:141], v[206:207], 0, s[4:5]
	s_mov_b32 m0, s40
	s_nop 0
	global_load_lds_dwordx4 v[140:141], off
	v_lshl_add_u64 v[140:141], v[222:223], 0, s[4:5]
	s_mov_b32 m0, s41
	s_nop 0
	global_load_lds_dwordx4 v[140:141], off
	v_pk_mul_f32 v[226:227], v[126:127], v[244:245]
	v_pk_mul_f32 v[228:229], v[128:129], v[244:245]
	v_pk_mul_f32 v[230:231], v[118:119], v[244:245]
	v_pk_mul_f32 v[232:233], v[120:121], v[244:245]
	v_exp_f32_e32 v226, v226
	v_exp_f32_e32 v227, v227
	v_exp_f32_e32 v228, v228
	v_exp_f32_e32 v229, v229
	v_exp_f32_e32 v230, v230
	v_exp_f32_e32 v231, v231
	v_exp_f32_e32 v232, v232
	v_exp_f32_e32 v233, v233
	v_pk_add_f32 v[226:227], v[226:227], 1.0 op_sel_hi:[1,0]
	v_pk_add_f32 v[228:229], v[228:229], 1.0 op_sel_hi:[1,0]
	v_pk_add_f32 v[230:231], v[230:231], 1.0 op_sel_hi:[1,0]
	v_pk_add_f32 v[232:233], v[232:233], 1.0 op_sel_hi:[1,0]
	v_rcp_f32_e32 v226, v226
	v_rcp_f32_e32 v227, v227
	v_rcp_f32_e32 v228, v228
	v_rcp_f32_e32 v229, v229
	v_rcp_f32_e32 v230, v230
	v_rcp_f32_e32 v231, v231
	v_rcp_f32_e32 v232, v232
	v_rcp_f32_e32 v233, v233
	v_pk_mul_f32 v[126:127], v[126:127], v[226:227]
	v_pk_mul_f32 v[128:129], v[128:129], v[228:229]
	v_pk_mul_f32 v[118:119], v[118:119], v[230:231]
	v_pk_mul_f32 v[120:121], v[120:121], v[232:233]
	v_pk_mul_f32 v[126:127], v[126:127], v[122:123]
	v_pk_mul_f32 v[128:129], v[128:129], v[124:125]
	v_pk_mul_f32 v[118:119], v[118:119], v[114:115]
	v_pk_mul_f32 v[120:121], v[120:121], v[116:117]
	v_cvt_pk_bf16_f32 v234, v126, v127
	v_cvt_pk_bf16_f32 v235, v128, v129
	v_cvt_pk_bf16_f32 v236, v118, v119
	v_cvt_pk_bf16_f32 v237, v120, v121
	global_store_dwordx4 v246, v[234:237], s[100:101]
	v_pk_mul_f32 v[226:227], v[110:111], v[244:245]
	v_pk_mul_f32 v[228:229], v[112:113], v[244:245]
	v_pk_mul_f32 v[230:231], v[102:103], v[244:245]
	v_pk_mul_f32 v[232:233], v[104:105], v[244:245]
	v_exp_f32_e32 v226, v226
	v_exp_f32_e32 v227, v227
	v_exp_f32_e32 v228, v228
	v_exp_f32_e32 v229, v229
	v_exp_f32_e32 v230, v230
	v_exp_f32_e32 v231, v231
	v_exp_f32_e32 v232, v232
	v_exp_f32_e32 v233, v233
	v_pk_add_f32 v[226:227], v[226:227], 1.0 op_sel_hi:[1,0]
	v_pk_add_f32 v[228:229], v[228:229], 1.0 op_sel_hi:[1,0]
	v_pk_add_f32 v[230:231], v[230:231], 1.0 op_sel_hi:[1,0]
	v_pk_add_f32 v[232:233], v[232:233], 1.0 op_sel_hi:[1,0]
	v_rcp_f32_e32 v226, v226
	v_rcp_f32_e32 v227, v227
	v_rcp_f32_e32 v228, v228
	v_rcp_f32_e32 v229, v229
	v_rcp_f32_e32 v230, v230
	v_rcp_f32_e32 v231, v231
	v_rcp_f32_e32 v232, v232
	v_rcp_f32_e32 v233, v233
	v_pk_mul_f32 v[110:111], v[110:111], v[226:227]
	v_pk_mul_f32 v[112:113], v[112:113], v[228:229]
	v_pk_mul_f32 v[102:103], v[102:103], v[230:231]
	v_pk_mul_f32 v[104:105], v[104:105], v[232:233]
	v_pk_mul_f32 v[110:111], v[110:111], v[106:107]
	v_pk_mul_f32 v[112:113], v[112:113], v[108:109]
	v_pk_mul_f32 v[102:103], v[102:103], v[98:99]
	v_pk_mul_f32 v[104:105], v[104:105], v[100:101]
	v_cvt_pk_bf16_f32 v238, v110, v111
	v_cvt_pk_bf16_f32 v239, v112, v113
	v_cvt_pk_bf16_f32 v240, v102, v103
	v_cvt_pk_bf16_f32 v241, v104, v105
	v_add_u32_e32 v243, 0x16000, v246
	global_store_dwordx4 v243, v[238:241], s[100:101]
	s_waitcnt vmcnt(10)
	s_waitcnt lgkmcnt(0)
	s_barrier
	s_setprio 1
	s_waitcnt lgkmcnt(0)
	v_mfma_f32_16x16x32_bf16 v[62:65], v[146:149], v[182:185], v[62:65]
	v_pk_mul_f32 v[226:227], v[94:95], v[244:245]
	v_pk_mul_f32 v[228:229], v[96:97], v[244:245]
	v_mfma_f32_16x16x32_bf16 v[54:57], v[154:157], v[182:185], v[54:57]
	v_pk_mul_f32 v[230:231], v[86:87], v[244:245]
	v_pk_mul_f32 v[232:233], v[88:89], v[244:245]
	v_mfma_f32_16x16x32_bf16 v[46:49], v[146:149], v[190:193], v[46:49]
	v_exp_f32_e32 v226, v226
	v_exp_f32_e32 v227, v227
	v_exp_f32_e32 v228, v228
	v_mfma_f32_16x16x32_bf16 v[38:41], v[154:157], v[190:193], v[38:41]
	v_exp_f32_e32 v229, v229
	v_exp_f32_e32 v230, v230
	v_mfma_f32_16x16x32_bf16 v[30:33], v[146:149], v[198:201], v[30:33]
	v_exp_f32_e32 v231, v231
	v_exp_f32_e32 v232, v232
	v_mfma_f32_16x16x32_bf16 v[22:25], v[154:157], v[198:201], v[22:25]
	v_exp_f32_e32 v233, v233
	v_pk_add_f32 v[226:227], v[226:227], 1.0 op_sel_hi:[1,0]
	v_pk_add_f32 v[228:229], v[228:229], 1.0 op_sel_hi:[1,0]
	v_mfma_f32_16x16x32_bf16 v[14:17], v[146:149], v[214:217], v[14:17]
	v_pk_add_f32 v[230:231], v[230:231], 1.0 op_sel_hi:[1,0]
	v_pk_add_f32 v[232:233], v[232:233], 1.0 op_sel_hi:[1,0]
	v_mfma_f32_16x16x32_bf16 v[6:9], v[154:157], v[214:217], v[6:9]
	v_rcp_f32_e32 v226, v226
	v_rcp_f32_e32 v227, v227
	v_rcp_f32_e32 v228, v228
	v_mfma_f32_16x16x32_bf16 v[62:65], v[150:153], v[186:189], v[62:65]
	v_rcp_f32_e32 v229, v229
	v_rcp_f32_e32 v230, v230
	v_mfma_f32_16x16x32_bf16 v[54:57], v[158:161], v[186:189], v[54:57]
	v_rcp_f32_e32 v231, v231
	v_rcp_f32_e32 v232, v232
	v_mfma_f32_16x16x32_bf16 v[46:49], v[150:153], v[194:197], v[46:49]
	v_rcp_f32_e32 v233, v233
	v_pk_mul_f32 v[94:95], v[94:95], v[226:227]
	v_pk_mul_f32 v[96:97], v[96:97], v[228:229]
	v_mfma_f32_16x16x32_bf16 v[38:41], v[158:161], v[194:197], v[38:41]
	v_pk_mul_f32 v[86:87], v[86:87], v[230:231]
	v_pk_mul_f32 v[88:89], v[88:89], v[232:233]
	v_mfma_f32_16x16x32_bf16 v[30:33], v[150:153], v[210:213], v[30:33]
	v_pk_mul_f32 v[94:95], v[94:95], v[90:91]
	v_pk_mul_f32 v[96:97], v[96:97], v[92:93]
	v_mfma_f32_16x16x32_bf16 v[22:25], v[158:161], v[210:213], v[22:25]
	v_pk_mul_f32 v[86:87], v[86:87], v[82:83]
	v_pk_mul_f32 v[88:89], v[88:89], v[84:85]
	v_cvt_pk_bf16_f32 v234, v94, v95
	v_mfma_f32_16x16x32_bf16 v[14:17], v[150:153], v[218:221], v[14:17]
	v_cvt_pk_bf16_f32 v235, v96, v97
	v_cvt_pk_bf16_f32 v236, v86, v87
	v_mfma_f32_16x16x32_bf16 v[6:9], v[158:161], v[218:221], v[6:9]
	v_cvt_pk_bf16_f32 v237, v88, v89
	v_add_u32_e32 v242, 0x2c000, v246
	global_store_dwordx4 v242, v[234:237], s[100:101]
	s_setprio 0
	s_setprio 1
	v_mfma_f32_16x16x32_bf16 v[58:61], v[166:169], v[182:185], v[58:61]
	v_pk_mul_f32 v[226:227], v[78:79], v[244:245]
	v_pk_mul_f32 v[228:229], v[80:81], v[244:245]
	v_mfma_f32_16x16x32_bf16 v[50:53], v[174:177], v[182:185], v[50:53]
	v_pk_mul_f32 v[230:231], v[70:71], v[244:245]
	v_pk_mul_f32 v[232:233], v[72:73], v[244:245]
	v_mfma_f32_16x16x32_bf16 v[42:45], v[166:169], v[190:193], v[42:45]
	v_exp_f32_e32 v226, v226
	v_exp_f32_e32 v227, v227
	v_exp_f32_e32 v228, v228
	v_mfma_f32_16x16x32_bf16 v[34:37], v[174:177], v[190:193], v[34:37]
	v_exp_f32_e32 v229, v229
	v_exp_f32_e32 v230, v230
	v_mfma_f32_16x16x32_bf16 v[26:29], v[166:169], v[198:201], v[26:29]
	v_exp_f32_e32 v231, v231
	v_exp_f32_e32 v232, v232
	v_mfma_f32_16x16x32_bf16 v[18:21], v[174:177], v[198:201], v[18:21]
	v_exp_f32_e32 v233, v233
	v_pk_add_f32 v[226:227], v[226:227], 1.0 op_sel_hi:[1,0]
	v_pk_add_f32 v[228:229], v[228:229], 1.0 op_sel_hi:[1,0]
	v_mfma_f32_16x16x32_bf16 v[10:13], v[166:169], v[214:217], v[10:13]
	v_pk_add_f32 v[230:231], v[230:231], 1.0 op_sel_hi:[1,0]
	v_pk_add_f32 v[232:233], v[232:233], 1.0 op_sel_hi:[1,0]
	v_mfma_f32_16x16x32_bf16 v[2:5], v[174:177], v[214:217], v[2:5]
	v_rcp_f32_e32 v226, v226
	v_rcp_f32_e32 v227, v227
	v_rcp_f32_e32 v228, v228
	v_mfma_f32_16x16x32_bf16 v[58:61], v[170:173], v[186:189], v[58:61]
	v_rcp_f32_e32 v229, v229
	v_rcp_f32_e32 v230, v230
	v_mfma_f32_16x16x32_bf16 v[50:53], v[178:181], v[186:189], v[50:53]
	v_rcp_f32_e32 v231, v231
	v_rcp_f32_e32 v232, v232
	v_mfma_f32_16x16x32_bf16 v[42:45], v[170:173], v[194:197], v[42:45]
	v_rcp_f32_e32 v233, v233
	v_pk_mul_f32 v[78:79], v[78:79], v[226:227]
	v_pk_mul_f32 v[80:81], v[80:81], v[228:229]
	v_mfma_f32_16x16x32_bf16 v[34:37], v[178:181], v[194:197], v[34:37]
	v_pk_mul_f32 v[70:71], v[70:71], v[230:231]
	v_pk_mul_f32 v[72:73], v[72:73], v[232:233]
	v_mfma_f32_16x16x32_bf16 v[26:29], v[170:173], v[210:213], v[26:29]
	v_pk_mul_f32 v[78:79], v[78:79], v[74:75]
	v_pk_mul_f32 v[80:81], v[80:81], v[76:77]
	v_mfma_f32_16x16x32_bf16 v[18:21], v[178:181], v[210:213], v[18:21]
	v_pk_mul_f32 v[70:71], v[70:71], v[66:67]
	v_pk_mul_f32 v[72:73], v[72:73], v[68:69]
	v_cvt_pk_bf16_f32 v238, v78, v79
	v_mfma_f32_16x16x32_bf16 v[10:13], v[170:173], v[218:221], v[10:13]
	v_cvt_pk_bf16_f32 v239, v80, v81
	v_cvt_pk_bf16_f32 v240, v70, v71
	v_mfma_f32_16x16x32_bf16 v[2:5], v[178:181], v[218:221], v[2:5]
	v_cvt_pk_bf16_f32 v241, v72, v73
	v_add_u32_e32 v243, 0x42000, v246
	global_store_dwordx4 v243, v[238:241], s[100:101]
	s_setprio 0
	s_barrier
	s_add_i32 s50, s50, 2
	s_add_u32 s20, s20, 0x100
	s_addc_u32 s21, s21, 0
	s_add_u32 s48, s48, 0x100
	s_addc_u32 s49, s49, 0
	s_and_b64 vcc, exec, s[10:11]
	s_cbranch_vccz .LBB0_687
	s_barrier
.LBB0_687:
	v_pk_mul_f32 v[226:227], v[62:63], v[244:245]
	v_pk_mul_f32 v[228:229], v[64:65], v[244:245]
	v_pk_mul_f32 v[230:231], v[54:55], v[244:245]
	v_pk_mul_f32 v[232:233], v[56:57], v[244:245]
	v_exp_f32_e32 v226, v226
	v_exp_f32_e32 v227, v227
	v_exp_f32_e32 v228, v228
	v_exp_f32_e32 v229, v229
	v_exp_f32_e32 v230, v230
	v_exp_f32_e32 v231, v231
	v_exp_f32_e32 v232, v232
	v_exp_f32_e32 v233, v233
	v_pk_add_f32 v[226:227], v[226:227], 1.0 op_sel_hi:[1,0]
	v_pk_add_f32 v[228:229], v[228:229], 1.0 op_sel_hi:[1,0]
	v_pk_add_f32 v[230:231], v[230:231], 1.0 op_sel_hi:[1,0]
	v_pk_add_f32 v[232:233], v[232:233], 1.0 op_sel_hi:[1,0]
	v_rcp_f32_e32 v226, v226
	v_rcp_f32_e32 v227, v227
	v_rcp_f32_e32 v228, v228
	v_rcp_f32_e32 v229, v229
	v_rcp_f32_e32 v230, v230
	v_rcp_f32_e32 v231, v231
	v_rcp_f32_e32 v232, v232
	v_rcp_f32_e32 v233, v233
	v_pk_mul_f32 v[62:63], v[62:63], v[226:227]
	v_pk_mul_f32 v[64:65], v[64:65], v[228:229]
	v_pk_mul_f32 v[54:55], v[54:55], v[230:231]
	v_pk_mul_f32 v[56:57], v[56:57], v[232:233]
	v_pk_mul_f32 v[62:63], v[62:63], v[58:59]
	v_pk_mul_f32 v[64:65], v[64:65], v[60:61]
	v_pk_mul_f32 v[54:55], v[54:55], v[50:51]
	v_pk_mul_f32 v[56:57], v[56:57], v[52:53]
	v_cvt_pk_bf16_f32 v234, v62, v63
	v_cvt_pk_bf16_f32 v235, v64, v65
	v_cvt_pk_bf16_f32 v236, v54, v55
	v_cvt_pk_bf16_f32 v237, v56, v57
	v_add_u32_e32 v242, 0xb0000, v246
	global_store_dwordx4 v242, v[234:237], s[100:101]
	v_pk_mul_f32 v[226:227], v[46:47], v[244:245]
	v_pk_mul_f32 v[228:229], v[48:49], v[244:245]
	v_pk_mul_f32 v[230:231], v[38:39], v[244:245]
	v_pk_mul_f32 v[232:233], v[40:41], v[244:245]
	v_exp_f32_e32 v226, v226
	v_exp_f32_e32 v227, v227
	v_exp_f32_e32 v228, v228
	v_exp_f32_e32 v229, v229
	v_exp_f32_e32 v230, v230
	v_exp_f32_e32 v231, v231
	v_exp_f32_e32 v232, v232
	v_exp_f32_e32 v233, v233
	v_pk_add_f32 v[226:227], v[226:227], 1.0 op_sel_hi:[1,0]
	v_pk_add_f32 v[228:229], v[228:229], 1.0 op_sel_hi:[1,0]
	v_pk_add_f32 v[230:231], v[230:231], 1.0 op_sel_hi:[1,0]
	v_pk_add_f32 v[232:233], v[232:233], 1.0 op_sel_hi:[1,0]
	v_rcp_f32_e32 v226, v226
	v_rcp_f32_e32 v227, v227
	v_rcp_f32_e32 v228, v228
	v_rcp_f32_e32 v229, v229
	v_rcp_f32_e32 v230, v230
	v_rcp_f32_e32 v231, v231
	v_rcp_f32_e32 v232, v232
	v_rcp_f32_e32 v233, v233
	v_pk_mul_f32 v[46:47], v[46:47], v[226:227]
	v_pk_mul_f32 v[48:49], v[48:49], v[228:229]
	v_pk_mul_f32 v[38:39], v[38:39], v[230:231]
	v_pk_mul_f32 v[40:41], v[40:41], v[232:233]
	v_pk_mul_f32 v[46:47], v[46:47], v[42:43]
	v_pk_mul_f32 v[48:49], v[48:49], v[44:45]
	v_pk_mul_f32 v[38:39], v[38:39], v[34:35]
	v_pk_mul_f32 v[40:41], v[40:41], v[36:37]
	v_cvt_pk_bf16_f32 v238, v46, v47
	v_cvt_pk_bf16_f32 v239, v48, v49
	v_cvt_pk_bf16_f32 v240, v38, v39
	v_cvt_pk_bf16_f32 v241, v40, v41
	v_add_u32_e32 v243, 0xc6000, v246
	global_store_dwordx4 v243, v[238:241], s[100:101]
	v_pk_mul_f32 v[226:227], v[30:31], v[244:245]
	v_pk_mul_f32 v[228:229], v[32:33], v[244:245]
	v_pk_mul_f32 v[230:231], v[22:23], v[244:245]
	v_pk_mul_f32 v[232:233], v[24:25], v[244:245]
	v_exp_f32_e32 v226, v226
	v_exp_f32_e32 v227, v227
	v_exp_f32_e32 v228, v228
	v_exp_f32_e32 v229, v229
	v_exp_f32_e32 v230, v230
	v_exp_f32_e32 v231, v231
	v_exp_f32_e32 v232, v232
	v_exp_f32_e32 v233, v233
	v_pk_add_f32 v[226:227], v[226:227], 1.0 op_sel_hi:[1,0]
	v_pk_add_f32 v[228:229], v[228:229], 1.0 op_sel_hi:[1,0]
	v_pk_add_f32 v[230:231], v[230:231], 1.0 op_sel_hi:[1,0]
	v_pk_add_f32 v[232:233], v[232:233], 1.0 op_sel_hi:[1,0]
	v_rcp_f32_e32 v226, v226
	v_rcp_f32_e32 v227, v227
	v_rcp_f32_e32 v228, v228
	v_rcp_f32_e32 v229, v229
	v_rcp_f32_e32 v230, v230
	v_rcp_f32_e32 v231, v231
	v_rcp_f32_e32 v232, v232
	v_rcp_f32_e32 v233, v233
	v_pk_mul_f32 v[30:31], v[30:31], v[226:227]
	v_pk_mul_f32 v[32:33], v[32:33], v[228:229]
	v_pk_mul_f32 v[22:23], v[22:23], v[230:231]
	v_pk_mul_f32 v[24:25], v[24:25], v[232:233]
	v_pk_mul_f32 v[30:31], v[30:31], v[26:27]
	v_pk_mul_f32 v[32:33], v[32:33], v[28:29]
	v_pk_mul_f32 v[22:23], v[22:23], v[18:19]
	v_pk_mul_f32 v[24:25], v[24:25], v[20:21]
	v_cvt_pk_bf16_f32 v234, v30, v31
	v_cvt_pk_bf16_f32 v235, v32, v33
	v_cvt_pk_bf16_f32 v236, v22, v23
	v_cvt_pk_bf16_f32 v237, v24, v25
	v_add_u32_e32 v242, 0xdc000, v246
	global_store_dwordx4 v242, v[234:237], s[100:101]
	v_pk_mul_f32 v[226:227], v[14:15], v[244:245]
	v_pk_mul_f32 v[228:229], v[16:17], v[244:245]
	v_pk_mul_f32 v[230:231], v[6:7], v[244:245]
	v_pk_mul_f32 v[232:233], v[8:9], v[244:245]
	v_exp_f32_e32 v226, v226
	v_exp_f32_e32 v227, v227
	v_exp_f32_e32 v228, v228
	v_exp_f32_e32 v229, v229
	v_exp_f32_e32 v230, v230
	v_exp_f32_e32 v231, v231
	v_exp_f32_e32 v232, v232
	v_exp_f32_e32 v233, v233
	v_pk_add_f32 v[226:227], v[226:227], 1.0 op_sel_hi:[1,0]
	v_pk_add_f32 v[228:229], v[228:229], 1.0 op_sel_hi:[1,0]
	v_pk_add_f32 v[230:231], v[230:231], 1.0 op_sel_hi:[1,0]
	v_pk_add_f32 v[232:233], v[232:233], 1.0 op_sel_hi:[1,0]
	v_rcp_f32_e32 v226, v226
	v_rcp_f32_e32 v227, v227
	v_rcp_f32_e32 v228, v228
	v_rcp_f32_e32 v229, v229
	v_rcp_f32_e32 v230, v230
	v_rcp_f32_e32 v231, v231
	v_rcp_f32_e32 v232, v232
	v_rcp_f32_e32 v233, v233
	v_pk_mul_f32 v[14:15], v[14:15], v[226:227]
	v_pk_mul_f32 v[16:17], v[16:17], v[228:229]
	v_pk_mul_f32 v[6:7], v[6:7], v[230:231]
	v_pk_mul_f32 v[8:9], v[8:9], v[232:233]
	v_pk_mul_f32 v[14:15], v[14:15], v[10:11]
	v_pk_mul_f32 v[16:17], v[16:17], v[12:13]
	v_pk_mul_f32 v[6:7], v[6:7], v[2:3]
	v_pk_mul_f32 v[8:9], v[8:9], v[4:5]
	v_cvt_pk_bf16_f32 v238, v14, v15
	v_cvt_pk_bf16_f32 v239, v16, v17
	v_cvt_pk_bf16_f32 v240, v6, v7
	v_cvt_pk_bf16_f32 v241, v8, v9
	v_add_u32_e32 v243, 0xf2000, v246
	global_store_dwordx4 v243, v[238:241], s[100:101]
	s_andn2_b64 vcc, exec, s[6:7]
	s_mov_b64 s[20:21], -1
	s_cbranch_vccnz .LBB0_680
	s_andn2_b64 vcc, exec, s[8:9]
	s_cbranch_vccnz .LBB0_679
	s_barrier
	s_branch .LBB0_679
